# on top of the DMA placement: static s_setprio 1 for the GLA MFMA-role waves (4-7) during the scan
# baseline (speedup 1.0000x reference)
; #define GLA_BAR() do { asm volatile("s_waitcnt lgkmcnt(0)" ::: "memory"); __builtin_amdgcn_s_barrier(); asm volatile("" ::: "memory"); } while (0)
; __device__ __forceinline__ void gla_mma(const Params& p, unsigned char* lds, int l, int item, int tid) {
;     unsigned char* ws = p.ws;
;     const int wid = __builtin_amdgcn_readfirstlane(tid >> 6), lane = tid & 63, lr = lane & 15, q4 = lane >> 4;
;     const int b = item >> 3, h = (item >> 1) & 3, dir = item & 1;
;     const bf16_t* Z = (const bf16_t*)(ws + WS_Z); bf16_t* OX = (bf16_t*)(ws + WS_OX); bf16_t* MIX = (bf16_t*)(ws + WS_MIX);
;     const bf16_t* qin = (const bf16_t*)(lds + L_QIN); const bf16_t* kin = (const bf16_t*)(lds + L_KIN); const bf16_t* qout = (const bf16_t*)(lds + L_QOUT); const bf16_t* koutT = (const bf16_t*)(lds + L_KOUTT);
;     const float* decs = (const float*)(lds + L_DEC); float* red = (float*)(lds + L_RED); const bf16_t* vraw = (const bf16_t*)(lds + L_VRAW);
;     const int vq = wid & 3;
;     const int ocol = h * 128 + 32 * vq + 8 * q4;
;     f32x4 ng[2];
; #pragma unroll
;     for (int vb = 0; vb < 2; ++vb) ng[vb] = *(const f32x4*)(p.gla_norm_g + (size_t)l * 512 + ocol + 4 * vb);
;     f32x4 accS[2][4];
; #pragma unroll
;     for (int vb = 0; vb < 2; ++vb)
; #pragma unroll
;         for (int i = 0; i < 4; ++i) accS[vb][i] = (f32x4){0.f, 0.f, 0.f, 0.f};
;     GLA_BAR();
;     for (int s = -1; s < 64; ++s) {
;         const int tok0 = b * SEQ + CHUNK(s < 0 ? 0 : s) * 64;
;     ...
;         if (s == 32) __syncthreads();
; PHASE_FN void gla_item(const Params& p, unsigned char* lds, int l, int item) {
;     ...
;     if (tid < 256) gla_prep(p, lds, l, item, tid); else gla_mma(p, lds, l, item, tid);
.LBB0_257:
	s_andn2_b64 vcc, exec, s[24:25]
	s_cbranch_vccnz .LBB0_353
	v_mov_b32_e32 v106, v206
	s_movk_i32 s4, 0xff
	v_and_b32_e32 v108, 15, v106
	v_cmp_lt_i32_e32 vcc, s4, v106
	v_bfe_u32 v107, v106, 4, 2
	v_and_b32_e32 v112, 3, v106
	v_lshlrev_b32_e32 v111, 2, v108
	s_and_saveexec_b64 s[4:5], vcc
	s_xor_b64 s[24:25], exec, s[4:5]
	s_cbranch_execz .LBB0_282
	s_setprio 1
	v_readfirstlane_b32 s4, v106
	s_bfe_u32 s6, s4, 0x20006
	v_lshlrev_b32_e32 v9, 3, v107
	v_readlane_b32 s4, v247, 38
	v_readlane_b32 s36, v248, 0
	v_readlane_b32 s50, v248, 14
	v_or_b32_e32 v0, s4, v9
	v_readlane_b32 s4, v246, 56
	v_readlane_b32 s51, v248, 15
	s_lshl_b32 s4, s4, 11
	s_mov_b64 s[26:27], s[50:51]
	v_lshl_or_b32 v8, s6, 5, v0
	v_readlane_b32 s5, v246, 57
	s_add_u32 s4, s26, s4
	s_addc_u32 s5, s27, 0
	v_lshlrev_b32_e32 v4, 2, v8
	s_nop 1
	global_load_dwordx4 v[0:3], v4, s[4:5] offset:16
	s_nop 0
	global_load_dwordx4 v[4:7], v4, s[4:5]
	s_lshl_b32 s4, s6, 6
	v_lshlrev_b32_e32 v11, 2, v106
	s_add_i32 s4, s4, 0
	v_and_b32_e32 v11, 48, v11
	v_lshlrev_b32_e32 v12, 1, v112
	v_add3_u32 v11, s4, v11, v12
	v_readlane_b32 s4, v247, 36
	v_mul_u32_u24_e32 v143, 0x240, v107
	v_lshlrev_b32_e32 v152, 1, v8
	v_readlane_b32 s5, v247, 37
	v_lshl_add_u32 v14, v143, 1, 0
	v_lshlrev_b32_e32 v10, 2, v107
	s_waitcnt lgkmcnt(0)
	v_lshl_add_u64 v[136:137], s[4:5], 0, v[152:153]
	s_movk_i32 s4, 0xfb90
	v_mad_i32_i24 v144, v107, s4, v14
	s_lshl_b32 s4, s6, 8
	v_readlane_b32 s6, v246, 26
	v_readlane_b32 s7, v246, 27
	v_cmp_ge_u32_e32 vcc, v108, v10
	s_movk_i32 s5, 0x420
	v_lshl_add_u64 v[138:139], s[6:7], 0, v[152:153]
	v_cndmask_b32_e64 v28, 0, 1, vcc
	v_cmp_gt_u32_e32 vcc, v108, v10
	v_readlane_b32 s6, v247, 42
	v_readlane_b32 s7, v247, 43
	v_cndmask_b32_e64 v29, 0, 1, vcc
	v_readlane_b32 s42, v248, 6
	v_cndmask_b32_e64 v28, v29, v28, s[6:7]
	v_readlane_b32 s43, v248, 7
	v_mad_u32_u24 v19, v107, s5, v210
	v_mad_u32_u24 v20, v107, s5, v211
	v_mad_u32_u24 v21, v107, s5, v212
	v_mad_u32_u24 v22, v107, s5, v213
	v_mad_u32_u24 v23, v107, s5, v214
	v_mad_u32_u24 v24, v107, s5, v215
	v_and_b32_e32 v28, 1, v28
	v_readlane_b32 s5, v247, 52
	v_readlane_b32 s44, v248, 8
	v_readlane_b32 s45, v248, 9
	v_cmp_eq_u32_e64 s[42:43], 1, v28
	v_or_b32_e32 v28, s5, v10
	v_cmp_gt_u32_e64 s[44:45], v108, v28
	v_or_b32_e32 v28, 2, v10
	v_cmp_ge_u32_e32 vcc, v108, v28
	v_or_b32_e32 v16, 32, v10
	v_or_b32_e32 v10, 3, v10
	v_cndmask_b32_e64 v29, 0, 1, vcc
	v_cmp_gt_u32_e32 vcc, v108, v28
	v_readlane_b32 s46, v248, 10
	v_readlane_b32 s47, v248, 11
	v_cndmask_b32_e64 v28, 0, 1, vcc
	v_cndmask_b32_e64 v28, v28, v29, s[6:7]
	v_and_b32_e32 v28, 1, v28
	v_cmp_ge_u32_e32 vcc, v108, v10
	v_bfe_u32 v12, v106, 2, 2
	v_cmp_eq_u32_e64 s[46:47], 1, v28
	v_cndmask_b32_e64 v28, 0, 1, vcc
	v_cmp_gt_u32_e32 vcc, v108, v10
	v_mul_u32_u24_e32 v12, 0x48, v12
	v_and_b32_e32 v13, 12, v111
	v_cndmask_b32_e64 v10, 0, 1, vcc
	v_add_lshl_u32 v12, v13, v12, 1
	v_cndmask_b32_e64 v10, v10, v28, s[6:7]
	v_readlane_b32 s48, v248, 12
	v_readlane_b32 s49, v248, 13
	s_waitcnt lgkmcnt(0)
	s_barrier
	v_bitop3_b32 v15, v106, 63, 15 bitop3:0x6c
	v_add_u32_e32 v145, v14, v12
	v_bitop3_b32 v14, v106, 31, 15 bitop3:0x6c
	v_or_b32_e32 v25, 32, v108
	v_bitop3_b32 v26, v106, 15, v106 bitop3:0xc
	v_or_b32_e32 v27, 48, v108
	v_and_b32_e32 v10, 1, v10
	v_add_u32_e32 v146, 0, v12
	s_movk_i32 s5, 0x240
	v_mov_b32_e32 v52, v153
	v_mov_b32_e32 v53, v153
	v_mov_b32_e32 v54, v153
	v_mov_b32_e32 v55, v153
	v_readlane_b32 s40, v248, 4
	v_readlane_b32 s41, v248, 5
	v_readlane_b32 s50, v246, 43
	v_sub_u32_e32 v9, v144, v9
	v_mul_u32_u24_e32 v17, 0x108, v16
	v_mul_u32_u24_e32 v18, 0x420, v107
	v_or_b32_e32 v13, 16, v108
	v_cmp_eq_u32_e64 s[48:49], 1, v10
	v_mad_u32_u24 v147, v107, s5, v146
	v_mul_u32_u24_e32 v10, 0x90, v16
	s_movk_i32 s5, 0x90
	v_mul_u32_u24_e32 v12, 0x90, v108
	v_cndmask_b32_e64 v149, v15, v108, s[6:7]
	v_bitop3_b32 v15, v106, 47, 15 bitop3:0x6c
	v_cndmask_b32_e64 v151, v14, v25, s[6:7]
	v_cndmask_b32_e64 v162, v26, v27, s[6:7]
	v_add_u32_e32 v170, v11, v24
	v_mov_b64_e32 v[66:67], v[54:55]
	v_mov_b64_e32 v[44:45], v[52:53]
	v_mov_b64_e32 v[24:25], v[52:53]
	v_mov_b64_e32 v[70:71], v[54:55]
	v_mov_b64_e32 v[62:63], v[54:55]
	v_mov_b64_e32 v[40:41], v[52:53]
	v_mov_b64_e32 v[28:29], v[52:53]
	v_readlane_b32 s51, v246, 44
	v_add_u32_e32 v142, 0, v111
	v_cmp_eq_u32_e64 s[40:41], 0, v107
	v_mad_u32_u24 v148, v16, s5, v146
	v_cndmask_b32_e64 v150, v15, v13, s[6:7]
	s_movk_i32 s5, 0xffe0
	v_add_u32_e32 v163, v11, v18
	v_add_u32_e32 v164, v11, v17
	v_add_u32_e32 v165, v11, v19
	v_add_u32_e32 v166, v11, v20
	v_add_u32_e32 v167, v11, v21
	v_add_u32_e32 v168, v11, v22
	v_add_u32_e32 v169, v11, v23
	v_lshlrev_b32_e32 v152, 1, v8
	v_add_u32_e32 v171, v146, v10
	v_add_u32_e32 v172, v9, v12
	v_mov_b64_e32 v[64:65], v[52:53]
	v_mov_b64_e32 v[46:47], v[54:55]
	v_mov_b64_e32 v[26:27], v[54:55]
	v_mov_b64_e32 v[68:69], v[52:53]
	v_mov_b64_e32 v[60:61], v[52:53]
	v_mov_b64_e32 v[42:43], v[54:55]
	v_mov_b64_e32 v[30:31], v[54:55]
	v_readlane_b32 s37, v248, 1
	v_readlane_b32 s38, v248, 2
	v_readlane_b32 s39, v248, 3
	s_branch .LBB0_262

; __device__ __forceinline__ unsigned cvt_pk_bf16(float lo, float hi) { unsigned r; asm volatile("v_cvt_pk_bf16_f32 %0, %1, %2" : "=v"(r) : "v"(lo), "v"(hi)); return r; }
; __device__ __forceinline__ void gla_prep(const Params& p, unsigned char* lds, int l, int item, int tid) {
;     ...
;     c.tid = tid; c.wid = __builtin_amdgcn_readfirstlane(tid >> 6); const int lane = tid & 63; c.lr = lane & 15; c.q4 = lane >> 4;
;     c.b = item >> 3; c.h = (item >> 1) & 3; c.dir = item & 1; const int dir = c.dir;
;     c.Z = (const bf16_t*)(ws + WS_Z); c.DEC = (const bf16_t*)(ws + WS_DEC);
;     unsigned* flags = (unsigned*)(ws + WS_CTL);
;     c.myflag = flags + (size_t)(l * 128 + item) * 64; c.paflag = flags + (size_t)(l * 128 + (item ^ 1)) * 64;
;     c.qin = (bf16_t*)(lds + L_QIN); c.kin = (bf16_t*)(lds + L_KIN); c.qout = (bf16_t*)(lds + L_QOUT); c.koutT = (bf16_t*)(lds + L_KOUTT);
;     c.decs = (float*)(lds + L_DEC);
;     c.qraw = (bf16_t*)(lds + L_QRAW); c.kraw = (bf16_t*)(lds + L_KRAW); c.araw = (bf16_t*)(lds + L_ARAW); c.vraw = (bf16_t*)(lds + L_VRAW);
;     c.lrow = tid >> 3; c.lcs = (tid & 7) * 8; c.vrow = tid >> 4; c.vcs = (tid & 15) * 8; c.arow = tid >> 1; c.acs = (tid & 1) * 8;
;     c.ch = 16 * c.wid + c.lr;
;     { const float* w2 = (dir ? p.w_a2_bwd : p.w_a2_fwd) + (size_t)l * 16 * 256 + c.h * 64 + c.ch; u32x4 w = (u32x4){0u, 0u, 0u, 0u};
;       if (c.q4 < 2) { float t[8];
; #pragma unroll
;           for (int i = 0; i < 8; ++i) t[i] = w2[(8 * c.q4 + i) * 256];
;           w.x = cvt_pk_bf16(t[0], t[1]); w.y = cvt_pk_bf16(t[2], t[3]); w.z = cvt_pk_bf16(t[4], t[5]); w.w = cvt_pk_bf16(t[6], t[7]); }
;       c.w2f = __builtin_bit_cast(bf16x8, w); c.bias = (dir ? p.b_a_bwd : p.b_a_fwd)[l * 256 + c.h * 64 + c.ch]; }
; PHASE_FN void gla_item(const Params& p, unsigned char* lds, int l, int item) {
;     ...
;     if (tid < 256) gla_prep(p, lds, l, item, tid); else gla_mma(p, lds, l, item, tid);
.LBB0_282:
	s_setprio 0
	s_andn2_saveexec_b64 s[24:25], s[24:25]
	s_cbranch_execz .LBB0_352
	v_readfirstlane_b32 s5, v106
	s_ashr_i32 s4, s5, 6
	s_waitcnt vmcnt(0)
	v_mov_b32_e32 v0, 0
	v_lshl_or_b32 v64, s4, 4, v108
	v_cmp_gt_u32_e64 s[40:41], 2, v107
	v_mov_b32_e32 v1, v0
	v_mov_b32_e32 v2, v0
	v_mov_b32_e32 v3, v0
	s_and_saveexec_b64 s[26:27], s[40:41]
	v_readlane_b32 s14, v246, 56
	v_readlane_b32 s15, v246, 57
	s_cbranch_execz .LBB0_285
	s_lshl_b32 s6, s14, 14
	v_readlane_b32 s7, v247, 46
	s_add_u32 s6, s7, s6
	v_readlane_b32 s7, v247, 47
	v_ashrrev_i32_e32 v65, 31, v64
	s_addc_u32 s7, s7, 0
	v_lshl_add_u64 v[0:1], v[64:65], 2, s[6:7]
	v_lshlrev_b32_e32 v152, 13, v107
	v_lshl_add_u64 v[0:1], v[0:1], 0, v[152:153]
	s_movk_i32 s6, 0x1000
	v_add_co_u32_e32 v2, vcc, s6, v0
	s_nop 1
	v_addc_co_u32_e32 v3, vcc, 0, v1, vcc
	global_load_dword v4, v[0:1], off offset:1024
	global_load_dword v5, v[0:1], off offset:2048
	global_load_dword v6, v[2:3], off offset:3072
	global_load_dword v7, v[2:3], off offset:1024
	global_load_dword v8, v[0:1], off offset:3072
	s_nop 0
	global_load_dword v0, v[0:1], off
	s_nop 0
	global_load_dword v9, v[2:3], off
	s_nop 0
	global_load_dword v3, v[2:3], off offset:2048
	s_waitcnt vmcnt(2)
	v_cvt_pk_bf16_f32 v0, v0, v4
	v_cvt_pk_bf16_f32 v1, v5, v8
	s_waitcnt vmcnt(1)
	v_cvt_pk_bf16_f32 v2, v9, v7
	s_waitcnt vmcnt(0)
	v_cvt_pk_bf16_f32 v3, v3, v6
